# prep-GEMM epilogue: parameter vectors loaded once per tile instead of pointer+vector loads with waits in each of 8 store blocks
# baseline (speedup 1.0000x reference)
.LBB0_399:
	s_cmp_gt_i32 s66, 5
	s_cselect_b64 s[64:65], -1, 0
	s_cmp_gt_u32 s66, 7
	s_waitcnt vmcnt(5)
	v_lshl_add_u32 v70, s56, 8, v35
	v_or_b32_e32 v68, s57, v124
	s_cselect_b64 s[56:57], -1, 0
	s_add_i32 s24, s66, -6
	s_lshl_b64 s[54:55], s[24:25], 11
	s_lshl_b64 s[40:41], s[24:25], 25
	s_add_u32 s58, s70, s40
	s_addc_u32 s59, s71, s41
	s_add_i32 s24, s66, -4
	s_lshl_b64 s[52:53], s[24:25], 11
	s_lshl_b64 s[40:41], s[24:25], 25
	s_add_u32 s60, s68, s40
	v_ashrrev_i32_e32 v71, 31, v70
	s_addc_u32 s61, s69, s41
	s_waitcnt vmcnt(4)
	v_lshlrev_b64 v[72:73], 10, v[70:71]
	s_waitcnt vmcnt(3)
	v_lshl_add_u64 v[78:79], s[42:43], 0, v[72:73]
	v_lshl_add_u64 v[74:75], s[58:59], 0, v[72:73]
	v_lshl_add_u64 v[72:73], s[60:61], 0, v[72:73]
	s_cmp_gt_i32 s66, 7
	s_cbranch_scc1 .Lpp_skip
	s_cmp_gt_i32 s66, 3
	s_cbranch_scc1 .Lpp_a
	s_load_dwordx2 s[98:99], s[22:23], 0x28
	s_lshl_b32 s100, s66, 9
	s_waitcnt lgkmcnt(0)
	s_add_u32 s98, s98, s46
	s_addc_u32 s99, s99, s47
	s_add_u32 s98, s98, s100
	s_addc_u32 s99, s99, 0
	s_branch .Lpp_go
.Lpp_a:
	s_cmp_gt_i32 s66, 5
	s_cbranch_scc1 .Lpp_b
	s_load_dwordx2 s[98:99], s[22:23], 0x58
	s_waitcnt lgkmcnt(0)
	s_add_u32 s98, s98, s44
	s_addc_u32 s99, s99, s45
	s_add_u32 s98, s98, s52
	s_addc_u32 s99, s99, s53
	s_branch .Lpp_go
.Lpp_b:
	s_load_dwordx2 s[98:99], s[22:23], 0x68
	s_waitcnt lgkmcnt(0)
	s_add_u32 s98, s98, s44
	s_addc_u32 s99, s99, s45
	s_add_u32 s98, s98, s54
	s_addc_u32 s99, s99, s55
.Lpp_go:
	v_mov_b32_e32 v142, v68
	v_mov_b32_e32 v143, 0
	v_lshl_add_u64 v[142:143], v[142:143], 2, s[98:99]
	global_load_dwordx4 v[144:147], v[142:143], off
	global_load_dwordx4 v[148:151], v[142:143], off offset:16
	global_load_dwordx4 v[152:155], v[142:143], off offset:128
	global_load_dwordx4 v[156:159], v[142:143], off offset:144
	s_waitcnt vmcnt(0)
.Lpp_skip:
	s_mov_b64 s[40:41], -1
	s_and_b64 vcc, exec, s[38:39]
	s_cbranch_vccz .LBB0_409
	s_and_b64 vcc, exec, s[64:65]
	s_cbranch_vccz .LBB0_406
	s_and_b64 vcc, exec, s[56:57]
	s_cbranch_vccz .LBB0_403
	v_mov_b32_e32 v69, v34
	v_cvt_pk_f16_f32 v71, v64, v65
	v_lshl_add_u64 v[80:81], v[68:69], 1, v[78:79]
	global_store_dword v[80:81], v71, off
	s_mov_b64 s[40:41], 0
.LBB0_403:
	s_andn2_b64 vcc, exec, s[40:41]
	v_mov_b32_e32 v87, v63
	v_mov_b32_e32 v86, v62
	v_mov_b32_e32 v83, v61
	v_mov_b32_e32 v82, v60
	v_mov_b32_e32 v85, v67
	v_mov_b32_e32 v84, v66
	s_cbranch_vccnz .LBB0_405
	v_mov_b32_e32 v69, v34
	s_add_u32 s24, s40, s44
	s_addc_u32 s41, s41, s45
	s_add_u32 s40, s24, s54
	s_addc_u32 s41, s41, s55
	v_lshl_add_u64 v[76:77], v[68:69], 2, s[40:41]
	v_mov_b32_e32 v80, v144
	v_mov_b32_e32 v81, v145
	v_mov_b32_e32 v82, v146
	v_mov_b32_e32 v83, v147
	v_mov_b32_e32 v84, v148
	v_mov_b32_e32 v85, v149
	v_mov_b32_e32 v86, v150
	v_mov_b32_e32 v87, v151
	v_add_f32_e32 v71, v64, v80
	v_add_f32_e32 v76, v65, v81
	v_add_f32_e32 v77, v66, v82
	v_add_f32_e32 v80, v67, v83
	v_add_f32_e32 v81, v60, v84
	v_add_f32_e32 v82, v61, v85
	v_add_f32_e32 v83, v62, v86
	v_add_f32_e32 v84, v63, v87
	v_mul_f32_e32 v71, 0xbfb8aa3b, v71
	v_mul_f32_e32 v76, 0xbfb8aa3b, v76
	v_mul_f32_e32 v77, 0xbfb8aa3b, v77
	v_mul_f32_e32 v80, 0xbfb8aa3b, v80
	v_mul_f32_e32 v81, 0xbfb8aa3b, v81
	v_mul_f32_e32 v82, 0xbfb8aa3b, v82
	v_mul_f32_e32 v83, 0xbfb8aa3b, v83
	v_mul_f32_e32 v84, 0xbfb8aa3b, v84
	v_exp_f32_e32 v71, v71
	v_exp_f32_e32 v76, v76
	v_exp_f32_e32 v77, v77
	v_exp_f32_e32 v80, v80
	v_exp_f32_e32 v81, v81
	v_exp_f32_e32 v82, v82
	v_exp_f32_e32 v83, v83
	v_exp_f32_e32 v84, v84
	v_add_f32_e32 v71, 1.0, v71
	v_add_f32_e32 v76, 1.0, v76
	v_add_f32_e32 v77, 1.0, v77
	v_add_f32_e32 v80, 1.0, v80
	v_add_f32_e32 v81, 1.0, v81
	v_add_f32_e32 v86, 1.0, v82
	v_add_f32_e32 v87, 1.0, v83
	v_add_f32_e32 v88, 1.0, v84
	v_rcp_f32_e32 v71, v71
	v_rcp_f32_e32 v76, v76
	v_rcp_f32_e32 v84, v77
	v_rcp_f32_e32 v85, v80
	v_rcp_f32_e32 v82, v81
	v_rcp_f32_e32 v83, v86
	v_rcp_f32_e32 v86, v87
	v_rcp_f32_e32 v87, v88
	v_cvt_pk_f16_f32 v71, v71, v76
	v_lshl_add_u64 v[80:81], v[68:69], 1, v[74:75]
	global_store_dword v[80:81], v71, off

.LBB0_406:
	s_andn2_b64 vcc, exec, s[40:41]
	s_cbranch_vccnz .LBB0_408
	v_mov_b32_e32 v69, v34
	s_add_u32 s24, s40, s44
	s_addc_u32 s41, s41, s45
	s_add_u32 s40, s24, s52
	s_addc_u32 s41, s41, s53
	v_lshl_add_u64 v[76:77], v[68:69], 2, s[40:41]
	v_mov_b32_e32 v80, v144
	v_mov_b32_e32 v81, v145
	v_mov_b32_e32 v82, v146
	v_mov_b32_e32 v83, v147
	v_mov_b32_e32 v84, v148
	v_mov_b32_e32 v85, v149
	v_mov_b32_e32 v86, v150
	v_mov_b32_e32 v87, v151
	v_add_f32_e32 v71, v64, v80
	v_add_f32_e32 v76, v65, v81
	v_add_f32_e32 v77, v66, v82
	v_add_f32_e32 v80, v67, v83
	v_add_f32_e32 v81, v60, v84
	v_add_f32_e32 v82, v61, v85
	v_add_f32_e32 v83, v62, v86
	v_add_f32_e32 v84, v63, v87
	v_mul_f32_e32 v71, 0xbfb8aa3b, v71
	v_mul_f32_e32 v76, 0xbfb8aa3b, v76
	v_mul_f32_e32 v77, 0xbfb8aa3b, v77
	v_mul_f32_e32 v80, 0xbfb8aa3b, v80
	v_mul_f32_e32 v81, 0xbfb8aa3b, v81
	v_mul_f32_e32 v82, 0xbfb8aa3b, v82
	v_mul_f32_e32 v83, 0xbfb8aa3b, v83
	v_mul_f32_e32 v84, 0xbfb8aa3b, v84
	v_exp_f32_e32 v71, v71
	v_exp_f32_e32 v76, v76
	v_exp_f32_e32 v77, v77
	v_exp_f32_e32 v80, v80
	v_exp_f32_e32 v81, v81
	v_exp_f32_e32 v82, v82
	v_exp_f32_e32 v83, v83
	v_exp_f32_e32 v84, v84
	v_add_f32_e32 v71, 1.0, v71
	v_add_f32_e32 v85, 1.0, v76
	v_add_f32_e32 v86, 1.0, v77
	v_add_f32_e32 v87, 1.0, v80
	v_add_f32_e32 v88, 1.0, v81
	v_add_f32_e32 v89, 1.0, v82
	v_add_f32_e32 v90, 1.0, v83
	v_add_f32_e32 v84, 1.0, v84
	v_rcp_f32_e32 v76, v71
	v_rcp_f32_e32 v77, v85
	v_rcp_f32_e32 v80, v86
	v_rcp_f32_e32 v81, v87
	v_rcp_f32_e32 v82, v88
	v_rcp_f32_e32 v83, v89
	v_rcp_f32_e32 v86, v90
	v_rcp_f32_e32 v87, v84
	v_pk_mul_f32 v[76:77], v[76:77], s[34:35] op_sel_hi:[1,0]
	v_pk_mul_f32 v[84:85], v[80:81], s[34:35] op_sel_hi:[1,0]
	v_pk_mul_f32 v[82:83], v[82:83], s[34:35] op_sel_hi:[1,0]
	v_pk_mul_f32 v[86:87], v[86:87], s[34:35] op_sel_hi:[1,0]
	v_cvt_pk_f16_f32 v71, v76, v77
	v_lshl_add_u64 v[80:81], v[68:69], 1, v[72:73]
	global_store_dword v[80:81], v71, off

.LBB0_409:
	v_mov_b64_e32 v[76:77], s[30:31]
	s_lshl_b32 s24, s66, 7
	v_mad_i64_i32 v[76:77], vcc, v70, s89, v[76:77]
	s_lshl_b32 s66, s66, 8
	s_mov_b32 s67, s25
	v_lshl_add_u64 v[76:77], v[76:77], 0, s[66:67]
	s_andn2_b64 vcc, exec, s[40:41]
	s_mov_b64 s[40:41], 0x6400800
	v_lshl_add_u64 v[76:77], v[76:77], 0, s[40:41]
	s_cbranch_vccnz .LBB0_411
	v_mov_b32_e32 v69, v34
	s_add_u32 s66, s40, s46
	s_addc_u32 s67, s41, s47
	s_lshl_b64 s[40:41], s[24:25], 2
	s_add_u32 s40, s66, s40
	s_addc_u32 s41, s67, s41
	v_lshl_add_u64 v[84:85], v[68:69], 2, s[40:41]
	v_mov_b32_e32 v80, v144
	v_mov_b32_e32 v81, v145
	v_mov_b32_e32 v82, v146
	v_mov_b32_e32 v83, v147
	v_mov_b32_e32 v86, v148
	v_mov_b32_e32 v87, v149
	v_mov_b32_e32 v88, v150
	v_mov_b32_e32 v89, v151
	v_pk_mul_f32 v[64:65], v[64:65], v[80:81]
	v_pk_mul_f32 v[84:85], v[66:67], v[82:83]
	v_pk_mul_f32 v[82:83], v[60:61], v[86:87]
	v_pk_mul_f32 v[86:87], v[62:63], v[88:89]
	v_cvt_pk_f16_f32 v60, v64, v65
	v_lshl_add_u64 v[80:81], v[68:69], 1, v[76:77]
	global_store_dword v[80:81], v60, off
.LBB0_411:
	v_cvt_pk_f16_f32 v62, v86, v87
	v_cvt_pk_f16_f32 v61, v82, v83
	v_cvt_pk_f16_f32 v60, v84, v85
	global_store_dwordx3 v[80:81], v[60:62], off offset:4
	s_mov_b64 s[66:67], -1
	s_andn2_b64 vcc, exec, s[38:39]
	v_cndmask_b32_e64 v60, 0, 1, s[38:39]
	v_cmp_ne_u32_e64 s[40:41], 1, v60
	v_cndmask_b32_e64 v60, 0, 1, s[64:65]
	v_cmp_ne_u32_e64 s[38:39], 1, v60
	s_cbranch_vccnz .LBB0_421
	s_and_b64 vcc, exec, s[38:39]
	s_mov_b64 s[64:65], -1
	s_cbranch_vccnz .LBB0_418
	s_andn2_b64 vcc, exec, s[56:57]
	s_cbranch_vccnz .LBB0_415
	v_mov_b32_e32 v69, v34
	v_lshl_add_u64 v[62:63], v[68:69], 1, v[78:79]
	v_cvt_pk_f16_f32 v64, v56, v57
	v_lshl_add_u64 v[60:61], v[62:63], 0, 64
	s_mov_b64 s[64:65], 0
	global_store_dword v[62:63], v64, off offset:64
.LBB0_415:
	s_andn2_b64 vcc, exec, s[64:65]
	v_mov_b32_e32 v63, v55
	v_mov_b32_e32 v62, v54
	v_mov_b32_e32 v65, v53
	v_mov_b32_e32 v64, v52
	v_mov_b32_e32 v67, v59
	v_mov_b32_e32 v66, v58
	s_cbranch_vccnz .LBB0_417
	v_mov_b32_e32 v69, v34
	v_lshl_add_u64 v[74:75], v[68:69], 1, v[74:75]
	s_add_u32 s64, s64, s44
	s_addc_u32 s65, s65, s45
	s_add_u32 s64, s64, s54
	s_addc_u32 s65, s65, s55
	v_lshl_add_u64 v[64:65], v[68:69], 2, s[64:65]
	v_mov_b32_e32 v60, v152
	v_mov_b32_e32 v61, v153
	v_mov_b32_e32 v62, v154
	v_mov_b32_e32 v63, v155
	s_nop 0
	v_mov_b32_e32 v64, v156
	v_mov_b32_e32 v65, v157
	v_mov_b32_e32 v66, v158
	v_mov_b32_e32 v67, v159
	v_add_f32_e32 v60, v56, v60
	v_add_f32_e32 v61, v57, v61
	v_add_f32_e32 v62, v58, v62
	v_add_f32_e32 v63, v59, v63
	v_add_f32_e32 v64, v52, v64
	v_add_f32_e32 v65, v53, v65
	v_add_f32_e32 v66, v54, v66
	v_add_f32_e32 v67, v55, v67
	v_mul_f32_e32 v60, 0xbfb8aa3b, v60
	v_mul_f32_e32 v61, 0xbfb8aa3b, v61
	v_mul_f32_e32 v62, 0xbfb8aa3b, v62
	v_mul_f32_e32 v63, 0xbfb8aa3b, v63
	v_mul_f32_e32 v64, 0xbfb8aa3b, v64
	v_mul_f32_e32 v65, 0xbfb8aa3b, v65
	v_mul_f32_e32 v66, 0xbfb8aa3b, v66
	v_mul_f32_e32 v67, 0xbfb8aa3b, v67
	v_exp_f32_e32 v60, v60
	v_exp_f32_e32 v61, v61
	v_exp_f32_e32 v62, v62
	v_exp_f32_e32 v63, v63
	v_exp_f32_e32 v64, v64
	v_exp_f32_e32 v65, v65
	v_exp_f32_e32 v66, v66
	v_exp_f32_e32 v67, v67
	v_add_f32_e32 v60, 1.0, v60
	v_add_f32_e32 v61, 1.0, v61
	v_add_f32_e32 v62, 1.0, v62
	v_add_f32_e32 v63, 1.0, v63
	v_add_f32_e32 v64, 1.0, v64
	v_add_f32_e32 v65, 1.0, v65
	v_add_f32_e32 v69, 1.0, v66
	v_add_f32_e32 v71, 1.0, v67
	v_rcp_f32_e32 v60, v60
	v_rcp_f32_e32 v61, v61
	v_rcp_f32_e32 v66, v62
	v_rcp_f32_e32 v67, v63
	v_rcp_f32_e32 v64, v64
	v_rcp_f32_e32 v65, v65
	v_rcp_f32_e32 v62, v69
	v_rcp_f32_e32 v63, v71
	v_cvt_pk_f16_f32 v69, v60, v61
	v_lshl_add_u64 v[60:61], v[74:75], 0, 64
	global_store_dword v[74:75], v69, off offset:64

.LBB0_418:
	s_andn2_b64 vcc, exec, s[64:65]
	s_cbranch_vccnz .LBB0_420
	v_mov_b32_e32 v69, v34
	v_lshl_add_u64 v[72:73], v[68:69], 1, v[72:73]
	s_add_u32 s64, s64, s44
	s_addc_u32 s65, s65, s45
	s_add_u32 s64, s64, s52
	s_addc_u32 s65, s65, s53
	v_lshl_add_u64 v[64:65], v[68:69], 2, s[64:65]
	v_mov_b32_e32 v60, v152
	v_mov_b32_e32 v61, v153
	v_mov_b32_e32 v62, v154
	v_mov_b32_e32 v63, v155
	s_nop 0
	v_mov_b32_e32 v64, v156
	v_mov_b32_e32 v65, v157
	v_mov_b32_e32 v66, v158
	v_mov_b32_e32 v67, v159
	v_add_f32_e32 v60, v56, v60
	v_add_f32_e32 v61, v57, v61
	v_add_f32_e32 v62, v58, v62
	v_add_f32_e32 v63, v59, v63
	v_add_f32_e32 v64, v52, v64
	v_add_f32_e32 v65, v53, v65
	v_add_f32_e32 v66, v54, v66
	v_add_f32_e32 v67, v55, v67
	v_mul_f32_e32 v60, 0xbfb8aa3b, v60
	v_mul_f32_e32 v61, 0xbfb8aa3b, v61
	v_mul_f32_e32 v62, 0xbfb8aa3b, v62
	v_mul_f32_e32 v63, 0xbfb8aa3b, v63
	v_mul_f32_e32 v64, 0xbfb8aa3b, v64
	v_mul_f32_e32 v65, 0xbfb8aa3b, v65
	v_mul_f32_e32 v66, 0xbfb8aa3b, v66
	v_mul_f32_e32 v67, 0xbfb8aa3b, v67
	v_exp_f32_e32 v60, v60
	v_exp_f32_e32 v61, v61
	v_exp_f32_e32 v62, v62
	v_exp_f32_e32 v63, v63
	v_exp_f32_e32 v64, v64
	v_exp_f32_e32 v65, v65
	v_exp_f32_e32 v66, v66
	v_exp_f32_e32 v67, v67
	v_add_f32_e32 v60, 1.0, v60
	v_add_f32_e32 v61, 1.0, v61
	v_add_f32_e32 v62, 1.0, v62
	v_add_f32_e32 v63, 1.0, v63
	v_add_f32_e32 v64, 1.0, v64
	v_add_f32_e32 v65, 1.0, v65
	v_add_f32_e32 v66, 1.0, v66
	v_add_f32_e32 v67, 1.0, v67
	v_rcp_f32_e32 v60, v60
	v_rcp_f32_e32 v61, v61
	v_rcp_f32_e32 v62, v62
	v_rcp_f32_e32 v63, v63
	v_rcp_f32_e32 v64, v64
	v_rcp_f32_e32 v65, v65
	v_rcp_f32_e32 v74, v66
	v_rcp_f32_e32 v75, v67
	v_pk_mul_f32 v[60:61], v[60:61], s[34:35] op_sel_hi:[1,0]
	v_pk_mul_f32 v[66:67], v[62:63], s[34:35] op_sel_hi:[1,0]
	v_pk_mul_f32 v[64:65], v[64:65], s[34:35] op_sel_hi:[1,0]
	v_pk_mul_f32 v[62:63], v[74:75], s[34:35] op_sel_hi:[1,0]
	v_cvt_pk_f16_f32 v69, v60, v61
	v_lshl_add_u64 v[60:61], v[72:73], 0, 64
	global_store_dword v[72:73], v69, off offset:64

.LBB0_421:
	s_andn2_b64 vcc, exec, s[66:67]
	s_cbranch_vccnz .LBB0_423
	v_mov_b32_e32 v69, v34
	v_lshl_add_u64 v[76:77], v[68:69], 1, v[76:77]
	s_add_u32 s66, s64, s46
	s_addc_u32 s67, s65, s47
	s_lshl_b64 s[64:65], s[24:25], 2
	s_add_u32 s64, s66, s64
	s_addc_u32 s65, s67, s65
	v_lshl_add_u64 v[64:65], v[68:69], 2, s[64:65]
	v_mov_b32_e32 v60, v152
	v_mov_b32_e32 v61, v153
	v_mov_b32_e32 v62, v154
	v_mov_b32_e32 v63, v155
	v_mov_b32_e32 v72, v156
	v_mov_b32_e32 v73, v157
	v_mov_b32_e32 v74, v158
	v_mov_b32_e32 v75, v159
	v_pk_mul_f32 v[56:57], v[56:57], v[60:61]
	v_pk_mul_f32 v[66:67], v[58:59], v[62:63]
	v_pk_mul_f32 v[64:65], v[52:53], v[72:73]
	v_pk_mul_f32 v[62:63], v[54:55], v[74:75]
	v_cvt_pk_f16_f32 v52, v56, v57
	v_lshl_add_u64 v[60:61], v[76:77], 0, 64
	global_store_dword v[76:77], v52, off offset:64

.LBB0_427:
	s_andn2_b64 vcc, exec, s[64:65]
	v_mov_b32_e32 v67, v47
	v_mov_b32_e32 v66, v46
	v_mov_b32_e32 v61, v45
	v_mov_b32_e32 v60, v44
	v_mov_b32_e32 v63, v51
	v_mov_b32_e32 v62, v50
	s_cbranch_vccnz .LBB0_429
	v_mov_b32_e32 v69, v34
	s_add_u32 s64, s64, s44
	s_addc_u32 s65, s65, s45
	s_add_u32 s64, s64, s54
	s_addc_u32 s65, s65, s55
	v_lshl_add_u64 v[64:65], v[68:69], 2, s[64:65]
	v_mov_b32_e32 v60, v144
	v_mov_b32_e32 v61, v145
	v_mov_b32_e32 v62, v146
	v_mov_b32_e32 v63, v147
	s_nop 0
	v_mov_b32_e32 v64, v148
	v_mov_b32_e32 v65, v149
	v_mov_b32_e32 v66, v150
	v_mov_b32_e32 v67, v151
	v_add_f32_e32 v57, v48, v60
	v_add_f32_e32 v60, v49, v61
	v_add_f32_e32 v61, v50, v62
	v_add_f32_e32 v62, v51, v63
	v_add_f32_e32 v63, v44, v64
	v_add_f32_e32 v64, v45, v65
	v_add_f32_e32 v65, v46, v66
	v_add_f32_e32 v66, v47, v67
	v_mul_f32_e32 v57, 0xbfb8aa3b, v57
	v_mul_f32_e32 v60, 0xbfb8aa3b, v60
	v_mul_f32_e32 v61, 0xbfb8aa3b, v61
	v_mul_f32_e32 v62, 0xbfb8aa3b, v62
	v_mul_f32_e32 v63, 0xbfb8aa3b, v63
	v_mul_f32_e32 v64, 0xbfb8aa3b, v64
	v_mul_f32_e32 v65, 0xbfb8aa3b, v65
	v_mul_f32_e32 v66, 0xbfb8aa3b, v66
	v_exp_f32_e32 v57, v57
	v_exp_f32_e32 v60, v60
	v_exp_f32_e32 v61, v61
	v_exp_f32_e32 v62, v62
	v_exp_f32_e32 v63, v63
	v_exp_f32_e32 v64, v64
	v_exp_f32_e32 v65, v65
	v_exp_f32_e32 v66, v66
	v_add_f32_e32 v57, 1.0, v57
	v_add_f32_e32 v60, 1.0, v60
	v_add_f32_e32 v61, 1.0, v61
	v_add_f32_e32 v67, 1.0, v62
	v_add_f32_e32 v71, 1.0, v63
	v_add_f32_e32 v64, 1.0, v64
	v_add_f32_e32 v65, 1.0, v65
	v_add_f32_e32 v72, 1.0, v66
	v_rcp_f32_e32 v57, v57
	v_rcp_f32_e32 v73, v60
	v_rcp_f32_e32 v62, v61
	v_rcp_f32_e32 v63, v67
	v_rcp_f32_e32 v60, v71
	v_rcp_f32_e32 v61, v64
	v_rcp_f32_e32 v66, v65
	v_rcp_f32_e32 v67, v72
	v_cvt_pk_f16_f32 v57, v57, v73
	v_lshl_add_u64 v[64:65], v[68:69], 1, v[54:55]
	global_store_dword v[64:65], v57, off

.LBB0_430:
	s_andn2_b64 vcc, exec, s[64:65]
	s_cbranch_vccnz .LBB0_432
	v_mov_b32_e32 v69, v34
	s_add_u32 s64, s64, s44
	s_addc_u32 s65, s65, s45
	s_add_u32 s64, s64, s52
	s_addc_u32 s65, s65, s53
	v_lshl_add_u64 v[64:65], v[68:69], 2, s[64:65]
	v_mov_b32_e32 v60, v144
	v_mov_b32_e32 v61, v145
	v_mov_b32_e32 v62, v146
	v_mov_b32_e32 v63, v147
	s_nop 0
	v_mov_b32_e32 v64, v148
	v_mov_b32_e32 v65, v149
	v_mov_b32_e32 v66, v150
	v_mov_b32_e32 v67, v151
	v_add_f32_e32 v57, v48, v60
	v_add_f32_e32 v60, v49, v61
	v_add_f32_e32 v61, v50, v62
	v_add_f32_e32 v62, v51, v63
	v_add_f32_e32 v63, v44, v64
	v_add_f32_e32 v64, v45, v65
	v_add_f32_e32 v65, v46, v66
	v_add_f32_e32 v66, v47, v67
	v_mul_f32_e32 v57, 0xbfb8aa3b, v57
	v_mul_f32_e32 v60, 0xbfb8aa3b, v60
	v_mul_f32_e32 v61, 0xbfb8aa3b, v61
	v_mul_f32_e32 v62, 0xbfb8aa3b, v62
	v_mul_f32_e32 v63, 0xbfb8aa3b, v63
	v_mul_f32_e32 v64, 0xbfb8aa3b, v64
	v_mul_f32_e32 v65, 0xbfb8aa3b, v65
	v_mul_f32_e32 v66, 0xbfb8aa3b, v66
	v_exp_f32_e32 v57, v57
	v_exp_f32_e32 v60, v60
	v_exp_f32_e32 v61, v61
	v_exp_f32_e32 v62, v62
	v_exp_f32_e32 v63, v63
	v_exp_f32_e32 v64, v64
	v_exp_f32_e32 v65, v65
	v_exp_f32_e32 v66, v66
	v_add_f32_e32 v57, 1.0, v57
	v_add_f32_e32 v67, 1.0, v60
	v_add_f32_e32 v71, 1.0, v61
	v_add_f32_e32 v72, 1.0, v62
	v_add_f32_e32 v73, 1.0, v63
	v_add_f32_e32 v74, 1.0, v64
	v_add_f32_e32 v75, 1.0, v65
	v_add_f32_e32 v76, 1.0, v66
	v_rcp_f32_e32 v60, v57
	v_rcp_f32_e32 v61, v67
	v_rcp_f32_e32 v62, v71
	v_rcp_f32_e32 v63, v72
	v_rcp_f32_e32 v64, v73
	v_rcp_f32_e32 v65, v74
	v_rcp_f32_e32 v66, v75
	v_rcp_f32_e32 v67, v76
	v_pk_mul_f32 v[72:73], v[60:61], s[34:35] op_sel_hi:[1,0]
	v_pk_mul_f32 v[62:63], v[62:63], s[34:35] op_sel_hi:[1,0]
	v_pk_mul_f32 v[60:61], v[64:65], s[34:35] op_sel_hi:[1,0]
	v_pk_mul_f32 v[66:67], v[66:67], s[34:35] op_sel_hi:[1,0]
	v_cvt_pk_f16_f32 v57, v72, v73
	v_lshl_add_u64 v[64:65], v[68:69], 1, v[52:53]
	global_store_dword v[64:65], v57, off

.LBB0_433:
	v_mov_b64_e32 v[72:73], s[30:31]
	v_mad_i64_i32 v[56:57], s[64:65], v56, s89, v[72:73]
	s_lshl_b32 s64, s24, 1
	s_mov_b32 s65, s25
	v_lshl_add_u64 v[56:57], v[56:57], 0, s[64:65]
	s_andn2_b64 vcc, exec, s[66:67]
	s_mov_b64 s[66:67], 0x6400800
	v_lshl_add_u64 v[56:57], v[56:57], 0, s[66:67]
	s_cbranch_vccnz .LBB0_435
	v_mov_b32_e32 v69, v34
	s_add_u32 s65, s66, s46
	s_addc_u32 s79, s67, s47
	s_lshl_b64 s[66:67], s[24:25], 2
	s_add_u32 s66, s65, s66
	s_addc_u32 s67, s79, s67
	v_lshl_add_u64 v[64:65], v[68:69], 2, s[66:67]
	v_mov_b32_e32 v60, v144
	v_mov_b32_e32 v61, v145
	v_mov_b32_e32 v62, v146
	v_mov_b32_e32 v63, v147
	s_nop 0
	v_mov_b32_e32 v64, v148
	v_mov_b32_e32 v65, v149
	v_mov_b32_e32 v66, v150
	v_mov_b32_e32 v67, v151
	v_pk_mul_f32 v[48:49], v[48:49], v[60:61]
	v_pk_mul_f32 v[62:63], v[50:51], v[62:63]
	v_pk_mul_f32 v[60:61], v[44:45], v[64:65]
	v_pk_mul_f32 v[66:67], v[46:47], v[66:67]
	v_cvt_pk_f16_f32 v44, v48, v49
	v_lshl_add_u64 v[64:65], v[68:69], 1, v[56:57]
	global_store_dword v[64:65], v44, off

.LBB0_439:
	s_andn2_b64 vcc, exec, s[66:67]
	v_mov_b32_e32 v47, v39
	v_mov_b32_e32 v46, v38
	v_mov_b32_e32 v49, v37
	v_mov_b32_e32 v48, v36
	v_mov_b32_e32 v51, v43
	v_mov_b32_e32 v50, v42
	s_cbranch_vccnz .LBB0_441
	v_mov_b32_e32 v69, v34
	v_lshl_add_u64 v[54:55], v[68:69], 1, v[54:55]
	s_add_u32 s65, s66, s44
	s_addc_u32 s67, s67, s45
	s_add_u32 s66, s65, s54
	s_addc_u32 s67, s67, s55
	v_lshl_add_u64 v[48:49], v[68:69], 2, s[66:67]
	v_mov_b32_e32 v44, v152
	v_mov_b32_e32 v45, v153
	v_mov_b32_e32 v46, v154
	v_mov_b32_e32 v47, v155
	s_nop 0
	v_mov_b32_e32 v48, v156
	v_mov_b32_e32 v49, v157
	v_mov_b32_e32 v50, v158
	v_mov_b32_e32 v51, v159
	v_add_f32_e32 v44, v40, v44
	v_add_f32_e32 v45, v41, v45
	v_add_f32_e32 v46, v42, v46
	v_add_f32_e32 v47, v43, v47
	v_add_f32_e32 v48, v36, v48
	v_add_f32_e32 v49, v37, v49
	v_add_f32_e32 v50, v38, v50
	v_add_f32_e32 v51, v39, v51
	v_mul_f32_e32 v44, 0xbfb8aa3b, v44
	v_mul_f32_e32 v45, 0xbfb8aa3b, v45
	v_mul_f32_e32 v46, 0xbfb8aa3b, v46
	v_mul_f32_e32 v47, 0xbfb8aa3b, v47
	v_mul_f32_e32 v48, 0xbfb8aa3b, v48
	v_mul_f32_e32 v49, 0xbfb8aa3b, v49
	v_mul_f32_e32 v50, 0xbfb8aa3b, v50
	v_mul_f32_e32 v51, 0xbfb8aa3b, v51
	v_exp_f32_e32 v44, v44
	v_exp_f32_e32 v45, v45
	v_exp_f32_e32 v46, v46
	v_exp_f32_e32 v47, v47
	v_exp_f32_e32 v48, v48
	v_exp_f32_e32 v49, v49
	v_exp_f32_e32 v50, v50
	v_exp_f32_e32 v51, v51
	v_add_f32_e32 v44, 1.0, v44
	v_add_f32_e32 v45, 1.0, v45
	v_add_f32_e32 v46, 1.0, v46
	v_add_f32_e32 v47, 1.0, v47
	v_add_f32_e32 v48, 1.0, v48
	v_add_f32_e32 v49, 1.0, v49
	v_add_f32_e32 v58, 1.0, v50
	v_add_f32_e32 v59, 1.0, v51
	v_rcp_f32_e32 v44, v44
	v_rcp_f32_e32 v45, v45
	v_rcp_f32_e32 v50, v46
	v_rcp_f32_e32 v51, v47
	v_rcp_f32_e32 v48, v48
	v_rcp_f32_e32 v49, v49
	v_rcp_f32_e32 v46, v58
	v_rcp_f32_e32 v47, v59
	v_cvt_pk_f16_f32 v58, v44, v45
	v_lshl_add_u64 v[44:45], v[54:55], 0, 64
	global_store_dword v[54:55], v58, off offset:64

.LBB0_442:
	s_andn2_b64 vcc, exec, s[66:67]
	s_cbranch_vccnz .LBB0_444
	v_mov_b32_e32 v69, v34
	v_lshl_add_u64 v[52:53], v[68:69], 1, v[52:53]
	s_add_u32 s65, s66, s44
	s_addc_u32 s67, s67, s45
	s_add_u32 s66, s65, s52
	s_addc_u32 s67, s67, s53
	v_lshl_add_u64 v[48:49], v[68:69], 2, s[66:67]
	v_mov_b32_e32 v44, v152
	v_mov_b32_e32 v45, v153
	v_mov_b32_e32 v46, v154
	v_mov_b32_e32 v47, v155
	s_nop 0
	v_mov_b32_e32 v48, v156
	v_mov_b32_e32 v49, v157
	v_mov_b32_e32 v50, v158
	v_mov_b32_e32 v51, v159
	v_add_f32_e32 v44, v40, v44
	v_add_f32_e32 v45, v41, v45
	v_add_f32_e32 v46, v42, v46
	v_add_f32_e32 v47, v43, v47
	v_add_f32_e32 v48, v36, v48
	v_add_f32_e32 v49, v37, v49
	v_add_f32_e32 v50, v38, v50
	v_add_f32_e32 v51, v39, v51
	v_mul_f32_e32 v44, 0xbfb8aa3b, v44
	v_mul_f32_e32 v45, 0xbfb8aa3b, v45
	v_mul_f32_e32 v46, 0xbfb8aa3b, v46
	v_mul_f32_e32 v47, 0xbfb8aa3b, v47
	v_mul_f32_e32 v48, 0xbfb8aa3b, v48
	v_mul_f32_e32 v49, 0xbfb8aa3b, v49
	v_mul_f32_e32 v50, 0xbfb8aa3b, v50
	v_mul_f32_e32 v51, 0xbfb8aa3b, v51
	v_exp_f32_e32 v44, v44
	v_exp_f32_e32 v45, v45
	v_exp_f32_e32 v46, v46
	v_exp_f32_e32 v47, v47
	v_exp_f32_e32 v48, v48
	v_exp_f32_e32 v49, v49
	v_exp_f32_e32 v50, v50
	v_exp_f32_e32 v51, v51
	v_add_f32_e32 v44, 1.0, v44
	v_add_f32_e32 v45, 1.0, v45
	v_add_f32_e32 v46, 1.0, v46
	v_add_f32_e32 v47, 1.0, v47
	v_add_f32_e32 v48, 1.0, v48
	v_add_f32_e32 v49, 1.0, v49
	v_add_f32_e32 v50, 1.0, v50
	v_add_f32_e32 v51, 1.0, v51
	v_rcp_f32_e32 v44, v44
	v_rcp_f32_e32 v45, v45
	v_rcp_f32_e32 v46, v46
	v_rcp_f32_e32 v47, v47
	v_rcp_f32_e32 v48, v48
	v_rcp_f32_e32 v49, v49
	v_rcp_f32_e32 v54, v50
	v_rcp_f32_e32 v55, v51
	v_pk_mul_f32 v[44:45], v[44:45], s[34:35] op_sel_hi:[1,0]
	v_pk_mul_f32 v[50:51], v[46:47], s[34:35] op_sel_hi:[1,0]
	v_pk_mul_f32 v[48:49], v[48:49], s[34:35] op_sel_hi:[1,0]
	v_pk_mul_f32 v[46:47], v[54:55], s[34:35] op_sel_hi:[1,0]
	v_cvt_pk_f16_f32 v54, v44, v45
	v_lshl_add_u64 v[44:45], v[52:53], 0, 64
	global_store_dword v[52:53], v54, off offset:64

.LBB0_445:
	s_andn2_b64 vcc, exec, s[66:67]
	s_cbranch_vccnz .LBB0_447
	v_mov_b32_e32 v69, v34
	v_lshl_add_u64 v[56:57], v[68:69], 1, v[56:57]
	s_add_u32 s65, s66, s46
	s_addc_u32 s79, s67, s47
	s_lshl_b64 s[66:67], s[24:25], 2
	s_add_u32 s66, s65, s66
	s_addc_u32 s67, s79, s67
	v_lshl_add_u64 v[48:49], v[68:69], 2, s[66:67]
	v_mov_b32_e32 v44, v152
	v_mov_b32_e32 v45, v153
	v_mov_b32_e32 v46, v154
	v_mov_b32_e32 v47, v155
	v_mov_b32_e32 v52, v156
	v_mov_b32_e32 v53, v157
	v_mov_b32_e32 v54, v158
	v_mov_b32_e32 v55, v159
	v_pk_mul_f32 v[40:41], v[40:41], v[44:45]
	v_pk_mul_f32 v[50:51], v[42:43], v[46:47]
	v_pk_mul_f32 v[48:49], v[36:37], v[52:53]
	v_pk_mul_f32 v[46:47], v[38:39], v[54:55]
	v_cvt_pk_f16_f32 v36, v40, v41
	v_lshl_add_u64 v[44:45], v[56:57], 0, 64
	global_store_dword v[56:57], v36, off offset:64

.LBB0_451:
	s_andn2_b64 vcc, exec, s[66:67]
	v_mov_b32_e32 v51, v29
	v_mov_b32_e32 v50, v28
	v_mov_b32_e32 v45, v27
	v_mov_b32_e32 v44, v26
	v_mov_b32_e32 v47, v33
	v_mov_b32_e32 v46, v32
	s_cbranch_vccnz .LBB0_453
	v_mov_b32_e32 v69, v34
	s_add_u32 s65, s66, s44
	s_addc_u32 s67, s67, s45
	s_add_u32 s66, s65, s54
	s_addc_u32 s67, s67, s55
	v_lshl_add_u64 v[48:49], v[68:69], 2, s[66:67]
	v_mov_b32_e32 v44, v144
	v_mov_b32_e32 v45, v145
	v_mov_b32_e32 v46, v146
	v_mov_b32_e32 v47, v147
	s_nop 0
	v_mov_b32_e32 v48, v148
	v_mov_b32_e32 v49, v149
	v_mov_b32_e32 v50, v150
	v_mov_b32_e32 v51, v151
	v_add_f32_e32 v41, v30, v44
	v_add_f32_e32 v44, v31, v45
	v_add_f32_e32 v45, v32, v46
	v_add_f32_e32 v46, v33, v47
	v_add_f32_e32 v47, v26, v48
	v_add_f32_e32 v48, v27, v49
	v_add_f32_e32 v49, v28, v50
	v_add_f32_e32 v50, v29, v51
	v_mul_f32_e32 v41, 0xbfb8aa3b, v41
	v_mul_f32_e32 v44, 0xbfb8aa3b, v44
	v_mul_f32_e32 v45, 0xbfb8aa3b, v45
	v_mul_f32_e32 v46, 0xbfb8aa3b, v46
	v_mul_f32_e32 v47, 0xbfb8aa3b, v47
	v_mul_f32_e32 v48, 0xbfb8aa3b, v48
	v_mul_f32_e32 v49, 0xbfb8aa3b, v49
	v_mul_f32_e32 v50, 0xbfb8aa3b, v50
	v_exp_f32_e32 v41, v41
	v_exp_f32_e32 v44, v44
	v_exp_f32_e32 v45, v45
	v_exp_f32_e32 v46, v46
	v_exp_f32_e32 v47, v47
	v_exp_f32_e32 v48, v48
	v_exp_f32_e32 v49, v49
	v_exp_f32_e32 v50, v50
	v_add_f32_e32 v41, 1.0, v41
	v_add_f32_e32 v44, 1.0, v44
	v_add_f32_e32 v45, 1.0, v45
	v_add_f32_e32 v51, 1.0, v46
	v_add_f32_e32 v52, 1.0, v47
	v_add_f32_e32 v48, 1.0, v48
	v_add_f32_e32 v49, 1.0, v49
	v_add_f32_e32 v53, 1.0, v50
	v_rcp_f32_e32 v41, v41
	v_rcp_f32_e32 v54, v44
	v_rcp_f32_e32 v46, v45
	v_rcp_f32_e32 v47, v51
	v_rcp_f32_e32 v44, v52
	v_rcp_f32_e32 v45, v48
	v_rcp_f32_e32 v50, v49
	v_rcp_f32_e32 v51, v53
	v_cvt_pk_f16_f32 v41, v41, v54
	v_lshl_add_u64 v[48:49], v[68:69], 1, v[38:39]
	global_store_dword v[48:49], v41, off

.LBB0_454:
	s_andn2_b64 vcc, exec, s[66:67]
	s_cbranch_vccnz .LBB0_456
	v_mov_b32_e32 v69, v34
	s_add_u32 s65, s66, s44
	s_addc_u32 s67, s67, s45
	s_add_u32 s66, s65, s52
	s_addc_u32 s67, s67, s53
	v_lshl_add_u64 v[48:49], v[68:69], 2, s[66:67]
	v_mov_b32_e32 v44, v144
	v_mov_b32_e32 v45, v145
	v_mov_b32_e32 v46, v146
	v_mov_b32_e32 v47, v147
	s_nop 0
	v_mov_b32_e32 v48, v148
	v_mov_b32_e32 v49, v149
	v_mov_b32_e32 v50, v150
	v_mov_b32_e32 v51, v151
	v_add_f32_e32 v41, v30, v44
	v_add_f32_e32 v44, v31, v45
	v_add_f32_e32 v45, v32, v46
	v_add_f32_e32 v46, v33, v47
	v_add_f32_e32 v47, v26, v48
	v_add_f32_e32 v48, v27, v49
	v_add_f32_e32 v49, v28, v50
	v_add_f32_e32 v50, v29, v51
	v_mul_f32_e32 v41, 0xbfb8aa3b, v41
	v_mul_f32_e32 v44, 0xbfb8aa3b, v44
	v_mul_f32_e32 v45, 0xbfb8aa3b, v45
	v_mul_f32_e32 v46, 0xbfb8aa3b, v46
	v_mul_f32_e32 v47, 0xbfb8aa3b, v47
	v_mul_f32_e32 v48, 0xbfb8aa3b, v48
	v_mul_f32_e32 v49, 0xbfb8aa3b, v49
	v_mul_f32_e32 v50, 0xbfb8aa3b, v50
	v_exp_f32_e32 v41, v41
	v_exp_f32_e32 v44, v44
	v_exp_f32_e32 v45, v45
	v_exp_f32_e32 v46, v46
	v_exp_f32_e32 v47, v47
	v_exp_f32_e32 v48, v48
	v_exp_f32_e32 v49, v49
	v_exp_f32_e32 v50, v50
	v_add_f32_e32 v41, 1.0, v41
	v_add_f32_e32 v51, 1.0, v44
	v_add_f32_e32 v52, 1.0, v45
	v_add_f32_e32 v53, 1.0, v46
	v_add_f32_e32 v54, 1.0, v47
	v_add_f32_e32 v55, 1.0, v48
	v_add_f32_e32 v56, 1.0, v49
	v_add_f32_e32 v57, 1.0, v50
	v_rcp_f32_e32 v44, v41
	v_rcp_f32_e32 v45, v51
	v_rcp_f32_e32 v46, v52
	v_rcp_f32_e32 v47, v53
	v_rcp_f32_e32 v48, v54
	v_rcp_f32_e32 v49, v55
	v_rcp_f32_e32 v50, v56
	v_rcp_f32_e32 v51, v57
	v_pk_mul_f32 v[52:53], v[44:45], s[34:35] op_sel_hi:[1,0]
	v_pk_mul_f32 v[46:47], v[46:47], s[34:35] op_sel_hi:[1,0]
	v_pk_mul_f32 v[44:45], v[48:49], s[34:35] op_sel_hi:[1,0]
	v_pk_mul_f32 v[50:51], v[50:51], s[34:35] op_sel_hi:[1,0]
	v_cvt_pk_f16_f32 v41, v52, v53
	v_lshl_add_u64 v[48:49], v[68:69], 1, v[36:37]
	global_store_dword v[48:49], v41, off

.LBB0_457:
	v_mov_b64_e32 v[52:53], s[30:31]
	v_mad_i64_i32 v[40:41], vcc, v40, s89, v[52:53]
	s_mov_b32 s65, s25
	v_lshl_add_u64 v[40:41], v[40:41], 0, s[64:65]
	s_andn2_b64 vcc, exec, s[66:67]
	s_mov_b64 s[66:67], 0x6400800
	v_lshl_add_u64 v[40:41], v[40:41], 0, s[66:67]
	s_cbranch_vccnz .LBB0_459
	v_mov_b32_e32 v69, v34
	s_add_u32 s65, s66, s46
	s_addc_u32 s79, s67, s47
	s_lshl_b64 s[66:67], s[24:25], 2
	s_add_u32 s66, s65, s66
	s_addc_u32 s67, s79, s67
	v_lshl_add_u64 v[48:49], v[68:69], 2, s[66:67]
	v_mov_b32_e32 v44, v144
	v_mov_b32_e32 v45, v145
	v_mov_b32_e32 v46, v146
	v_mov_b32_e32 v47, v147
	s_nop 0
	v_mov_b32_e32 v48, v148
	v_mov_b32_e32 v49, v149
	v_mov_b32_e32 v50, v150
	v_mov_b32_e32 v51, v151
	v_pk_mul_f32 v[30:31], v[30:31], v[44:45]
	v_pk_mul_f32 v[46:47], v[32:33], v[46:47]
	v_pk_mul_f32 v[44:45], v[26:27], v[48:49]
	v_pk_mul_f32 v[50:51], v[28:29], v[50:51]
	v_cvt_pk_f16_f32 v26, v30, v31
	v_lshl_add_u64 v[48:49], v[68:69], 1, v[40:41]
	global_store_dword v[48:49], v26, off

.LBB0_463:
	s_andn2_b64 vcc, exec, s[66:67]
	v_mov_b32_e32 v29, v21
	v_mov_b32_e32 v28, v20
	v_mov_b32_e32 v31, v19
	v_mov_b32_e32 v30, v18
	v_mov_b32_e32 v33, v25
	v_mov_b32_e32 v32, v24
	s_cbranch_vccnz .LBB0_465
	v_mov_b32_e32 v69, v34
	v_lshl_add_u64 v[38:39], v[68:69], 1, v[38:39]
	s_add_u32 s65, s66, s44
	s_addc_u32 s67, s67, s45
	s_add_u32 s66, s65, s54
	s_addc_u32 s67, s67, s55
	v_lshl_add_u64 v[30:31], v[68:69], 2, s[66:67]
	v_mov_b32_e32 v26, v152
	v_mov_b32_e32 v27, v153
	v_mov_b32_e32 v28, v154
	v_mov_b32_e32 v29, v155
	s_nop 0
	v_mov_b32_e32 v30, v156
	v_mov_b32_e32 v31, v157
	v_mov_b32_e32 v32, v158
	v_mov_b32_e32 v33, v159
	v_add_f32_e32 v26, v22, v26
	v_add_f32_e32 v27, v23, v27
	v_add_f32_e32 v28, v24, v28
	v_add_f32_e32 v29, v25, v29
	v_add_f32_e32 v30, v18, v30
	v_add_f32_e32 v31, v19, v31
	v_add_f32_e32 v32, v20, v32
	v_add_f32_e32 v33, v21, v33
	v_mul_f32_e32 v26, 0xbfb8aa3b, v26
	v_mul_f32_e32 v27, 0xbfb8aa3b, v27
	v_mul_f32_e32 v28, 0xbfb8aa3b, v28
	v_mul_f32_e32 v29, 0xbfb8aa3b, v29
	v_mul_f32_e32 v30, 0xbfb8aa3b, v30
	v_mul_f32_e32 v31, 0xbfb8aa3b, v31
	v_mul_f32_e32 v32, 0xbfb8aa3b, v32
	v_mul_f32_e32 v33, 0xbfb8aa3b, v33
	v_exp_f32_e32 v26, v26
	v_exp_f32_e32 v27, v27
	v_exp_f32_e32 v28, v28
	v_exp_f32_e32 v29, v29
	v_exp_f32_e32 v30, v30
	v_exp_f32_e32 v31, v31
	v_exp_f32_e32 v32, v32
	v_exp_f32_e32 v33, v33
	v_add_f32_e32 v26, 1.0, v26
	v_add_f32_e32 v27, 1.0, v27
	v_add_f32_e32 v28, 1.0, v28
	v_add_f32_e32 v29, 1.0, v29
	v_add_f32_e32 v30, 1.0, v30
	v_add_f32_e32 v31, 1.0, v31
	v_add_f32_e32 v42, 1.0, v32
	v_add_f32_e32 v43, 1.0, v33
	v_rcp_f32_e32 v26, v26
	v_rcp_f32_e32 v27, v27
	v_rcp_f32_e32 v32, v28
	v_rcp_f32_e32 v33, v29
	v_rcp_f32_e32 v30, v30
	v_rcp_f32_e32 v31, v31
	v_rcp_f32_e32 v28, v42
	v_rcp_f32_e32 v29, v43
	v_cvt_pk_f16_f32 v42, v26, v27
	v_lshl_add_u64 v[26:27], v[38:39], 0, 64
	global_store_dword v[38:39], v42, off offset:64

.LBB0_466:
	s_andn2_b64 vcc, exec, s[66:67]
	s_cbranch_vccnz .LBB0_468
	v_mov_b32_e32 v69, v34
	v_lshl_add_u64 v[36:37], v[68:69], 1, v[36:37]
	s_add_u32 s65, s66, s44
	s_addc_u32 s67, s67, s45
	s_add_u32 s66, s65, s52
	s_addc_u32 s67, s67, s53
	v_lshl_add_u64 v[30:31], v[68:69], 2, s[66:67]
	v_mov_b32_e32 v26, v152
	v_mov_b32_e32 v27, v153
	v_mov_b32_e32 v28, v154
	v_mov_b32_e32 v29, v155
	s_nop 0
	v_mov_b32_e32 v30, v156
	v_mov_b32_e32 v31, v157
	v_mov_b32_e32 v32, v158
	v_mov_b32_e32 v33, v159
	v_add_f32_e32 v26, v22, v26
	v_add_f32_e32 v27, v23, v27
	v_add_f32_e32 v28, v24, v28
	v_add_f32_e32 v29, v25, v29
	v_add_f32_e32 v30, v18, v30
	v_add_f32_e32 v31, v19, v31
	v_add_f32_e32 v32, v20, v32
	v_add_f32_e32 v33, v21, v33
	v_mul_f32_e32 v26, 0xbfb8aa3b, v26
	v_mul_f32_e32 v27, 0xbfb8aa3b, v27
	v_mul_f32_e32 v28, 0xbfb8aa3b, v28
	v_mul_f32_e32 v29, 0xbfb8aa3b, v29
	v_mul_f32_e32 v30, 0xbfb8aa3b, v30
	v_mul_f32_e32 v31, 0xbfb8aa3b, v31
	v_mul_f32_e32 v32, 0xbfb8aa3b, v32
	v_mul_f32_e32 v33, 0xbfb8aa3b, v33
	v_exp_f32_e32 v26, v26
	v_exp_f32_e32 v27, v27
	v_exp_f32_e32 v28, v28
	v_exp_f32_e32 v29, v29
	v_exp_f32_e32 v30, v30
	v_exp_f32_e32 v31, v31
	v_exp_f32_e32 v32, v32
	v_exp_f32_e32 v33, v33
	v_add_f32_e32 v26, 1.0, v26
	v_add_f32_e32 v27, 1.0, v27
	v_add_f32_e32 v28, 1.0, v28
	v_add_f32_e32 v29, 1.0, v29
	v_add_f32_e32 v30, 1.0, v30
	v_add_f32_e32 v31, 1.0, v31
	v_add_f32_e32 v32, 1.0, v32
	v_add_f32_e32 v33, 1.0, v33
	v_rcp_f32_e32 v26, v26
	v_rcp_f32_e32 v27, v27
	v_rcp_f32_e32 v28, v28
	v_rcp_f32_e32 v29, v29
	v_rcp_f32_e32 v30, v30
	v_rcp_f32_e32 v31, v31
	v_rcp_f32_e32 v38, v32
	v_rcp_f32_e32 v39, v33
	v_pk_mul_f32 v[26:27], v[26:27], s[34:35] op_sel_hi:[1,0]
	v_pk_mul_f32 v[32:33], v[28:29], s[34:35] op_sel_hi:[1,0]
	v_pk_mul_f32 v[30:31], v[30:31], s[34:35] op_sel_hi:[1,0]
	v_pk_mul_f32 v[28:29], v[38:39], s[34:35] op_sel_hi:[1,0]
	v_cvt_pk_f16_f32 v38, v26, v27
	v_lshl_add_u64 v[26:27], v[36:37], 0, 64
	global_store_dword v[36:37], v38, off offset:64

.LBB0_469:
	s_andn2_b64 vcc, exec, s[66:67]
	s_cbranch_vccnz .LBB0_471
	v_mov_b32_e32 v69, v34
	v_lshl_add_u64 v[40:41], v[68:69], 1, v[40:41]
	s_add_u32 s65, s66, s46
	s_addc_u32 s79, s67, s47
	s_lshl_b64 s[66:67], s[24:25], 2
	s_add_u32 s66, s65, s66
	s_addc_u32 s67, s79, s67
	v_lshl_add_u64 v[30:31], v[68:69], 2, s[66:67]
	v_mov_b32_e32 v26, v152
	v_mov_b32_e32 v27, v153
	v_mov_b32_e32 v28, v154
	v_mov_b32_e32 v29, v155
	v_mov_b32_e32 v36, v156
	v_mov_b32_e32 v37, v157
	v_mov_b32_e32 v38, v158
	v_mov_b32_e32 v39, v159
	v_pk_mul_f32 v[22:23], v[22:23], v[26:27]
	v_pk_mul_f32 v[32:33], v[24:25], v[28:29]
	v_pk_mul_f32 v[30:31], v[18:19], v[36:37]
	v_pk_mul_f32 v[28:29], v[20:21], v[38:39]
	v_cvt_pk_f16_f32 v18, v22, v23
	v_lshl_add_u64 v[26:27], v[40:41], 0, 64
	global_store_dword v[40:41], v18, off offset:64

.LBB0_475:
	s_andn2_b64 vcc, exec, s[58:59]
	v_mov_b32_e32 v33, v13
	v_mov_b32_e32 v32, v12
	v_mov_b32_e32 v27, v11
	v_mov_b32_e32 v26, v10
	v_mov_b32_e32 v29, v17
	v_mov_b32_e32 v28, v16
	s_cbranch_vccnz .LBB0_477
	v_mov_b32_e32 v69, v34
	s_add_u32 s58, s58, s44
	s_addc_u32 s59, s59, s45
	s_add_u32 s58, s58, s54
	s_addc_u32 s59, s59, s55
	v_lshl_add_u64 v[30:31], v[68:69], 2, s[58:59]
	v_mov_b32_e32 v26, v144
	v_mov_b32_e32 v27, v145
	v_mov_b32_e32 v28, v146
	v_mov_b32_e32 v29, v147
	s_nop 0
	v_mov_b32_e32 v30, v148
	v_mov_b32_e32 v31, v149
	v_mov_b32_e32 v32, v150
	v_mov_b32_e32 v33, v151
	v_add_f32_e32 v23, v14, v26
	v_add_f32_e32 v26, v15, v27
	v_add_f32_e32 v27, v16, v28
	v_add_f32_e32 v28, v17, v29
	v_add_f32_e32 v29, v10, v30
	v_add_f32_e32 v30, v11, v31
	v_add_f32_e32 v31, v12, v32
	v_add_f32_e32 v32, v13, v33
	v_mul_f32_e32 v23, 0xbfb8aa3b, v23
	v_mul_f32_e32 v26, 0xbfb8aa3b, v26
	v_mul_f32_e32 v27, 0xbfb8aa3b, v27
	v_mul_f32_e32 v28, 0xbfb8aa3b, v28
	v_mul_f32_e32 v29, 0xbfb8aa3b, v29
	v_mul_f32_e32 v30, 0xbfb8aa3b, v30
	v_mul_f32_e32 v31, 0xbfb8aa3b, v31
	v_mul_f32_e32 v32, 0xbfb8aa3b, v32
	v_exp_f32_e32 v23, v23
	v_exp_f32_e32 v26, v26
	v_exp_f32_e32 v27, v27
	v_exp_f32_e32 v28, v28
	v_exp_f32_e32 v29, v29
	v_exp_f32_e32 v30, v30
	v_exp_f32_e32 v31, v31
	v_exp_f32_e32 v32, v32
	v_add_f32_e32 v23, 1.0, v23
	v_add_f32_e32 v26, 1.0, v26
	v_add_f32_e32 v27, 1.0, v27
	v_add_f32_e32 v33, 1.0, v28
	v_add_f32_e32 v36, 1.0, v29
	v_add_f32_e32 v30, 1.0, v30
	v_add_f32_e32 v31, 1.0, v31
	v_add_f32_e32 v37, 1.0, v32
	v_rcp_f32_e32 v23, v23
	v_rcp_f32_e32 v38, v26
	v_rcp_f32_e32 v28, v27
	v_rcp_f32_e32 v29, v33
	v_rcp_f32_e32 v26, v36
	v_rcp_f32_e32 v27, v30
	v_rcp_f32_e32 v32, v31
	v_rcp_f32_e32 v33, v37
	v_cvt_pk_f16_f32 v23, v23, v38
	v_lshl_add_u64 v[30:31], v[68:69], 1, v[20:21]
	global_store_dword v[30:31], v23, off

.LBB0_478:
	s_andn2_b64 vcc, exec, s[58:59]
	s_cbranch_vccnz .LBB0_480
	v_mov_b32_e32 v69, v34
	s_add_u32 s58, s58, s44
	s_addc_u32 s59, s59, s45
	s_add_u32 s58, s58, s52
	s_addc_u32 s59, s59, s53
	v_lshl_add_u64 v[30:31], v[68:69], 2, s[58:59]
	v_mov_b32_e32 v26, v144
	v_mov_b32_e32 v27, v145
	v_mov_b32_e32 v28, v146
	v_mov_b32_e32 v29, v147
	s_nop 0
	v_mov_b32_e32 v30, v148
	v_mov_b32_e32 v31, v149
	v_mov_b32_e32 v32, v150
	v_mov_b32_e32 v33, v151
	v_add_f32_e32 v23, v14, v26
	v_add_f32_e32 v26, v15, v27
	v_add_f32_e32 v27, v16, v28
	v_add_f32_e32 v28, v17, v29
	v_add_f32_e32 v29, v10, v30
	v_add_f32_e32 v30, v11, v31
	v_add_f32_e32 v31, v12, v32
	v_add_f32_e32 v32, v13, v33
	v_mul_f32_e32 v23, 0xbfb8aa3b, v23
	v_mul_f32_e32 v26, 0xbfb8aa3b, v26
	v_mul_f32_e32 v27, 0xbfb8aa3b, v27
	v_mul_f32_e32 v28, 0xbfb8aa3b, v28
	v_mul_f32_e32 v29, 0xbfb8aa3b, v29
	v_mul_f32_e32 v30, 0xbfb8aa3b, v30
	v_mul_f32_e32 v31, 0xbfb8aa3b, v31
	v_mul_f32_e32 v32, 0xbfb8aa3b, v32
	v_exp_f32_e32 v23, v23
	v_exp_f32_e32 v26, v26
	v_exp_f32_e32 v27, v27
	v_exp_f32_e32 v28, v28
	v_exp_f32_e32 v29, v29
	v_exp_f32_e32 v30, v30
	v_exp_f32_e32 v31, v31
	v_exp_f32_e32 v32, v32
	v_add_f32_e32 v23, 1.0, v23
	v_add_f32_e32 v33, 1.0, v26
	v_add_f32_e32 v36, 1.0, v27
	v_add_f32_e32 v37, 1.0, v28
	v_add_f32_e32 v38, 1.0, v29
	v_add_f32_e32 v39, 1.0, v30
	v_add_f32_e32 v40, 1.0, v31
	v_add_f32_e32 v41, 1.0, v32
	v_rcp_f32_e32 v26, v23
	v_rcp_f32_e32 v27, v33
	v_rcp_f32_e32 v28, v36
	v_rcp_f32_e32 v29, v37
	v_rcp_f32_e32 v30, v38
	v_rcp_f32_e32 v31, v39
	v_rcp_f32_e32 v32, v40
	v_rcp_f32_e32 v33, v41
	v_pk_mul_f32 v[36:37], v[26:27], s[34:35] op_sel_hi:[1,0]
	v_pk_mul_f32 v[28:29], v[28:29], s[34:35] op_sel_hi:[1,0]
	v_pk_mul_f32 v[26:27], v[30:31], s[34:35] op_sel_hi:[1,0]
	v_pk_mul_f32 v[32:33], v[32:33], s[34:35] op_sel_hi:[1,0]
	v_cvt_pk_f16_f32 v23, v36, v37
	v_lshl_add_u64 v[30:31], v[68:69], 1, v[18:19]
	global_store_dword v[30:31], v23, off

.LBB0_481:
	v_mov_b64_e32 v[36:37], s[30:31]
	v_mad_i64_i32 v[22:23], s[60:61], v22, s89, v[36:37]
	s_mov_b32 s65, s25
	v_lshl_add_u64 v[22:23], v[22:23], 0, s[64:65]
	s_andn2_b64 vcc, exec, s[58:59]
	s_mov_b64 s[58:59], 0x6400800
	v_lshl_add_u64 v[22:23], v[22:23], 0, s[58:59]
	s_cbranch_vccnz .LBB0_483
	v_mov_b32_e32 v69, v34
	s_add_u32 s60, s58, s46
	s_addc_u32 s61, s59, s47
	s_lshl_b64 s[58:59], s[24:25], 2
	s_add_u32 s58, s60, s58
	s_addc_u32 s59, s61, s59
	v_lshl_add_u64 v[30:31], v[68:69], 2, s[58:59]
	v_mov_b32_e32 v26, v144
	v_mov_b32_e32 v27, v145
	v_mov_b32_e32 v28, v146
	v_mov_b32_e32 v29, v147
	s_nop 0
	v_mov_b32_e32 v30, v148
	v_mov_b32_e32 v31, v149
	v_mov_b32_e32 v32, v150
	v_mov_b32_e32 v33, v151
	v_pk_mul_f32 v[14:15], v[14:15], v[26:27]
	v_pk_mul_f32 v[28:29], v[16:17], v[28:29]
	v_pk_mul_f32 v[26:27], v[10:11], v[30:31]
	v_pk_mul_f32 v[32:33], v[12:13], v[32:33]
	v_cvt_pk_f16_f32 v10, v14, v15
	v_lshl_add_u64 v[30:31], v[68:69], 1, v[22:23]
	global_store_dword v[30:31], v10, off

.LBB0_487:
	s_andn2_b64 vcc, exec, s[38:39]
	v_mov_b32_e32 v13, v9
	v_mov_b32_e32 v12, v8
	v_mov_b32_e32 v15, v7
	v_mov_b32_e32 v14, v6
	v_mov_b32_e32 v17, v5
	v_mov_b32_e32 v16, v4
	s_cbranch_vccnz .LBB0_489
	v_mov_b32_e32 v69, v34
	v_lshl_add_u64 v[20:21], v[68:69], 1, v[20:21]
	s_add_u32 s38, s38, s44
	s_addc_u32 s39, s39, s45
	s_add_u32 s38, s38, s54
	s_addc_u32 s39, s39, s55
	v_lshl_add_u64 v[14:15], v[68:69], 2, s[38:39]
	v_mov_b32_e32 v10, v152
	v_mov_b32_e32 v11, v153
	v_mov_b32_e32 v12, v154
	v_mov_b32_e32 v13, v155
	s_nop 0
	v_mov_b32_e32 v14, v156
	v_mov_b32_e32 v15, v157
	v_mov_b32_e32 v16, v158
	v_mov_b32_e32 v17, v159
	v_add_f32_e32 v10, v2, v10
	v_add_f32_e32 v11, v3, v11
	v_add_f32_e32 v12, v4, v12
	v_add_f32_e32 v13, v5, v13
	v_add_f32_e32 v14, v6, v14
	v_add_f32_e32 v15, v7, v15
	v_add_f32_e32 v16, v8, v16
	v_add_f32_e32 v17, v9, v17
	v_mul_f32_e32 v10, 0xbfb8aa3b, v10
	v_mul_f32_e32 v11, 0xbfb8aa3b, v11
	v_mul_f32_e32 v12, 0xbfb8aa3b, v12
	v_mul_f32_e32 v13, 0xbfb8aa3b, v13
	v_mul_f32_e32 v14, 0xbfb8aa3b, v14
	v_mul_f32_e32 v15, 0xbfb8aa3b, v15
	v_mul_f32_e32 v16, 0xbfb8aa3b, v16
	v_mul_f32_e32 v17, 0xbfb8aa3b, v17
	v_exp_f32_e32 v10, v10
	v_exp_f32_e32 v11, v11
	v_exp_f32_e32 v12, v12
	v_exp_f32_e32 v13, v13
	v_exp_f32_e32 v14, v14
	v_exp_f32_e32 v15, v15
	v_exp_f32_e32 v16, v16
	v_exp_f32_e32 v17, v17
	v_add_f32_e32 v10, 1.0, v10
	v_add_f32_e32 v11, 1.0, v11
	v_add_f32_e32 v12, 1.0, v12
	v_add_f32_e32 v13, 1.0, v13
	v_add_f32_e32 v14, 1.0, v14
	v_add_f32_e32 v15, 1.0, v15
	v_add_f32_e32 v24, 1.0, v16
	v_add_f32_e32 v25, 1.0, v17
	v_rcp_f32_e32 v10, v10
	v_rcp_f32_e32 v11, v11
	v_rcp_f32_e32 v16, v12
	v_rcp_f32_e32 v17, v13
	v_rcp_f32_e32 v14, v14
	v_rcp_f32_e32 v15, v15
	v_rcp_f32_e32 v12, v24
	v_rcp_f32_e32 v13, v25
	v_cvt_pk_f16_f32 v24, v10, v11
	v_lshl_add_u64 v[10:11], v[20:21], 0, 64
	global_store_dword v[20:21], v24, off offset:64

.LBB0_490:
	s_andn2_b64 vcc, exec, s[38:39]
	s_cbranch_vccnz .LBB0_492
	v_mov_b32_e32 v69, v34
	v_lshl_add_u64 v[18:19], v[68:69], 1, v[18:19]
	s_add_u32 s38, s38, s44
	s_addc_u32 s39, s39, s45
	s_add_u32 s38, s38, s52
	s_addc_u32 s39, s39, s53
	v_lshl_add_u64 v[14:15], v[68:69], 2, s[38:39]
	v_mov_b32_e32 v10, v152
	v_mov_b32_e32 v11, v153
	v_mov_b32_e32 v12, v154
	v_mov_b32_e32 v13, v155
	s_nop 0
	v_mov_b32_e32 v14, v156
	v_mov_b32_e32 v15, v157
	v_mov_b32_e32 v16, v158
	v_mov_b32_e32 v17, v159
	v_add_f32_e32 v10, v2, v10
	v_add_f32_e32 v11, v3, v11
	v_add_f32_e32 v12, v4, v12
	v_add_f32_e32 v13, v5, v13
	v_add_f32_e32 v14, v6, v14
	v_add_f32_e32 v15, v7, v15
	v_add_f32_e32 v16, v8, v16
	v_add_f32_e32 v17, v9, v17
	v_mul_f32_e32 v10, 0xbfb8aa3b, v10
	v_mul_f32_e32 v11, 0xbfb8aa3b, v11
	v_mul_f32_e32 v12, 0xbfb8aa3b, v12
	v_mul_f32_e32 v13, 0xbfb8aa3b, v13
	v_mul_f32_e32 v14, 0xbfb8aa3b, v14
	v_mul_f32_e32 v15, 0xbfb8aa3b, v15
	v_mul_f32_e32 v16, 0xbfb8aa3b, v16
	v_mul_f32_e32 v17, 0xbfb8aa3b, v17
	v_exp_f32_e32 v10, v10
	v_exp_f32_e32 v11, v11
	v_exp_f32_e32 v12, v12
	v_exp_f32_e32 v13, v13
	v_exp_f32_e32 v14, v14
	v_exp_f32_e32 v15, v15
	v_exp_f32_e32 v16, v16
	v_exp_f32_e32 v17, v17
	v_add_f32_e32 v10, 1.0, v10
	v_add_f32_e32 v11, 1.0, v11
	v_add_f32_e32 v12, 1.0, v12
	v_add_f32_e32 v13, 1.0, v13
	v_add_f32_e32 v14, 1.0, v14
	v_add_f32_e32 v15, 1.0, v15
	v_add_f32_e32 v16, 1.0, v16
	v_add_f32_e32 v17, 1.0, v17
	v_rcp_f32_e32 v10, v10
	v_rcp_f32_e32 v11, v11
	v_rcp_f32_e32 v12, v12
	v_rcp_f32_e32 v13, v13
	v_rcp_f32_e32 v14, v14
	v_rcp_f32_e32 v15, v15
	v_rcp_f32_e32 v20, v16
	v_rcp_f32_e32 v21, v17
	v_pk_mul_f32 v[10:11], v[10:11], s[34:35] op_sel_hi:[1,0]
	v_pk_mul_f32 v[16:17], v[12:13], s[34:35] op_sel_hi:[1,0]
	v_pk_mul_f32 v[14:15], v[14:15], s[34:35] op_sel_hi:[1,0]
	v_pk_mul_f32 v[12:13], v[20:21], s[34:35] op_sel_hi:[1,0]
	v_cvt_pk_f16_f32 v20, v10, v11
	v_lshl_add_u64 v[10:11], v[18:19], 0, 64
	global_store_dword v[18:19], v20, off offset:64

.LBB0_493:
	s_andn2_b64 vcc, exec, s[40:41]
	s_cbranch_vccnz .LBB0_374
	v_mov_b32_e32 v69, v34
	v_lshl_add_u64 v[22:23], v[68:69], 1, v[22:23]
	s_add_u32 s40, s38, s46
	s_addc_u32 s41, s39, s47
	s_lshl_b64 s[38:39], s[24:25], 2
	s_add_u32 s38, s40, s38
	s_addc_u32 s39, s41, s39
	v_lshl_add_u64 v[14:15], v[68:69], 2, s[38:39]
	v_mov_b32_e32 v10, v152
	v_mov_b32_e32 v11, v153
	v_mov_b32_e32 v12, v154
	v_mov_b32_e32 v13, v155
	v_mov_b32_e32 v18, v156
	v_mov_b32_e32 v19, v157
	v_mov_b32_e32 v20, v158
	v_mov_b32_e32 v21, v159
	v_pk_mul_f32 v[2:3], v[2:3], v[10:11]
	v_pk_mul_f32 v[16:17], v[4:5], v[12:13]
	v_pk_mul_f32 v[14:15], v[6:7], v[18:19]
	v_pk_mul_f32 v[12:13], v[8:9], v[20:21]
	v_cvt_pk_f16_f32 v2, v2, v3
	v_lshl_add_u64 v[10:11], v[22:23], 0, 64
	global_store_dword v[22:23], v2, off offset:64
	s_branch .LBB0_374
